# stack2 + halo mini-GEMM: own fragment registers, chunk c+2 register prefetch issued at start of each half step
# speedup vs baseline: 1.0028x; 1.0028x over previous
; #define LAS __attribute__((address_space(3)))
; __device__ __forceinline__ void halo_gemm_unit(int unit, int tid, int lane, int wave, LAS unsigned char* lds, const bf16_t* __restrict__ XBp, const bf16_t* __restrict__ Wup, bf16_t* __restrict__ HALOp) {
;     ...
; #pragma unroll 1
;     for (int c = 0; c < 16; c += 2) {
;         { const int k2 = (c + 2 < 16) ? 64 * (c + 2) : 0;
; #pragma unroll
;           for (int i = 0; i < 2; ++i) ra0[i] = *(const v4u*)(gA[i] + k2);
; #pragma unroll
;           for (int i = 0; i < 4; ++i) rb0[i] = *(const v4u*)(gB[i] + k2);
;           HG_COMPUTE(lds);
; #pragma unroll
;           for (int i = 0; i < 2; ++i) *(LAS v4u*)(lds + HG_STAGE + lA[i]) = ra1[i];
; #pragma unroll
;           for (int i = 0; i < 4; ++i) *(LAS v4u*)(lds + HG_STAGE + lB[i]) = rb1[i];
;           __syncthreads(); }
;         { const int k3 = (c + 3 < 16) ? 64 * (c + 3) : 0;
; #pragma unroll
;           for (int i = 0; i < 2; ++i) ra1[i] = *(const v4u*)(gA[i] + k3);
; #pragma unroll
;           for (int i = 0; i < 4; ++i) rb1[i] = *(const v4u*)(gB[i] + k3);
;           HG_COMPUTE(lds + HG_STAGE);
;           if (c + 2 < 16) {
; #pragma unroll
;               for (int i = 0; i < 2; ++i) *(LAS v4u*)(lds + lA[i]) = ra0[i];
; #pragma unroll
;               for (int i = 0; i < 4; ++i) *(LAS v4u*)(lds + lB[i]) = rb0[i];
;           }
;           __syncthreads(); }
;     }
.LBB0_684:
	s_cmp_gt_u32 s12, 13
	s_cselect_b64 s[8:9], -1, 0
	s_sub_i32 s0, s10, 64
	s_cmp_lt_u32 s12, 14
	s_cselect_b32 s6, s0, 0
	s_lshl_b64 s[0:1], s[6:7], 1
	s_cmp_lt_u32 s12, 13
	s_cselect_b32 s6, s10, 0
	v_lshl_add_u64 v[110:111], v[124:125], 0, s[0:1]
	v_lshl_add_u64 v[90:91], v[114:115], 0, s[0:1]
	v_lshl_add_u64 v[94:95], v[116:117], 0, s[0:1]
	v_lshl_add_u64 v[106:107], v[122:123], 0, s[0:1]
	v_lshl_add_u64 v[98:99], v[118:119], 0, s[0:1]
	v_lshl_add_u64 v[102:103], v[120:121], 0, s[0:1]
	global_load_dwordx4 v[90:93], v[90:91], off
	s_nop 0
	global_load_dwordx4 v[94:97], v[94:95], off
	s_nop 0
	global_load_dwordx4 v[98:101], v[98:99], off
	s_nop 0
	global_load_dwordx4 v[102:105], v[102:103], off
	s_nop 0
	global_load_dwordx4 v[106:109], v[106:107], off
	s_nop 0
	global_load_dwordx4 v[110:113], v[110:111], off
	s_nop 0
	v_add_u32_e32 v139, 0, v132
	ds_read_b128 v[156:159], v139 offset:18432
	ds_read_b128 v[160:163], v133
	ds_read_b128 v[164:167], v133 offset:32
	ds_read_b128 v[168:171], v139 offset:18464
	ds_read_b128 v[172:175], v139 offset:23040
	ds_read_b128 v[176:179], v139 offset:23072
	s_waitcnt lgkmcnt(4)
	v_mfma_f32_32x32x16_bf16 v[50:65], v[156:159], v[160:163], v[50:65]
	s_waitcnt lgkmcnt(1)
	v_mfma_f32_32x32x16_bf16 v[34:49], v[172:175], v[160:163], v[34:49]
	ds_read_b128 v[160:163], v133 offset:4608
	ds_read_b128 v[140:143], v133 offset:4640
	s_and_b64 vcc, exec, s[8:9]
	s_waitcnt lgkmcnt(1)
	v_mfma_f32_32x32x16_bf16 v[18:33], v[156:159], v[160:163], v[18:33]
	v_mfma_f32_32x32x16_bf16 v[2:17], v[172:175], v[160:163], v[2:17]
	v_mfma_f32_32x32x16_bf16 v[50:65], v[168:171], v[164:167], v[50:65]
	v_mfma_f32_32x32x16_bf16 v[34:49], v[176:179], v[164:167], v[34:49]
	s_waitcnt lgkmcnt(0)
	v_mfma_f32_32x32x16_bf16 v[18:33], v[168:171], v[140:143], v[18:33]
	ds_read_b128 v[156:159], v139 offset:18496
	ds_read_b128 v[160:163], v133 offset:64
	ds_read_b128 v[164:167], v133 offset:96
	ds_read_b128 v[168:171], v139 offset:18528
	v_mfma_f32_32x32x16_bf16 v[2:17], v[176:179], v[140:143], v[2:17]
	ds_read_b128 v[172:175], v139 offset:23104
	ds_read_b128 v[140:143], v139 offset:23136
	s_waitcnt lgkmcnt(4)
	v_mfma_f32_32x32x16_bf16 v[50:65], v[156:159], v[160:163], v[50:65]
	s_waitcnt lgkmcnt(1)
	v_mfma_f32_32x32x16_bf16 v[34:49], v[172:175], v[160:163], v[34:49]
	ds_read_b128 v[160:163], v133 offset:4672
	ds_read_b128 v[146:149], v133 offset:4704
	s_waitcnt lgkmcnt(1)
	v_mfma_f32_32x32x16_bf16 v[18:33], v[156:159], v[160:163], v[18:33]
	v_mfma_f32_32x32x16_bf16 v[2:17], v[172:175], v[160:163], v[2:17]
	v_mfma_f32_32x32x16_bf16 v[50:65], v[168:171], v[164:167], v[50:65]
	v_mfma_f32_32x32x16_bf16 v[34:49], v[140:143], v[164:167], v[34:49]
	s_waitcnt lgkmcnt(0)
	v_mfma_f32_32x32x16_bf16 v[18:33], v[168:171], v[146:149], v[18:33]
	s_waitcnt vmcnt(11)
	ds_write_b128 v128, v[66:69] offset:55296
	s_waitcnt vmcnt(10)
	ds_write_b128 v129, v[70:73] offset:55296
	s_waitcnt vmcnt(9)
	ds_write_b128 v134, v[74:77] offset:55296
	s_waitcnt vmcnt(8)
	ds_write_b128 v135, v[78:81] offset:55296
	s_waitcnt vmcnt(6)
	ds_write_b128 v136, v[86:89] offset:55296
	ds_write_b128 v137, v[82:85] offset:55296
	s_waitcnt lgkmcnt(0)
	s_barrier
	s_lshl_b64 s[0:1], s[6:7], 1
	v_lshl_add_u64 v[150:151], v[124:125], 0, s[0:1]
	v_lshl_add_u64 v[86:87], v[122:123], 0, s[0:1]
	v_lshl_add_u64 v[66:67], v[114:115], 0, s[0:1]
	v_lshl_add_u64 v[70:71], v[116:117], 0, s[0:1]
	v_lshl_add_u64 v[78:79], v[120:121], 0, s[0:1]
	v_lshl_add_u64 v[74:75], v[118:119], 0, s[0:1]
	global_load_dwordx4 v[66:69], v[66:67], off
	s_nop 0
	global_load_dwordx4 v[70:73], v[70:71], off
	s_nop 0
	global_load_dwordx4 v[74:77], v[74:75], off
	s_nop 0
	global_load_dwordx4 v[78:81], v[78:79], off
	s_nop 0
	global_load_dwordx4 v[86:89], v[86:87], off
	s_nop 0
	global_load_dwordx4 v[82:85], v[150:151], off
	s_nop 0
	v_mfma_f32_32x32x16_bf16 v[2:17], v[140:143], v[146:149], v[2:17]
	ds_read_b128 v[180:183], v138 offset:55296
	ds_read_b128 v[184:187], v133 offset:55296
	ds_read_b128 v[188:191], v133 offset:55328
	ds_read_b128 v[192:195], v138 offset:55328
	ds_read_b128 v[196:199], v138 offset:59904
	ds_read_b128 v[200:203], v138 offset:59936
	s_waitcnt lgkmcnt(4)
	v_mfma_f32_32x32x16_bf16 v[50:65], v[180:183], v[184:187], v[50:65]
	s_waitcnt lgkmcnt(1)
	v_mfma_f32_32x32x16_bf16 v[34:49], v[196:199], v[184:187], v[34:49]
	ds_read_b128 v[184:187], v133 offset:59904
	ds_read_b128 v[140:143], v133 offset:59936
	s_waitcnt lgkmcnt(1)
	v_mfma_f32_32x32x16_bf16 v[18:33], v[180:183], v[184:187], v[18:33]
	v_mfma_f32_32x32x16_bf16 v[2:17], v[196:199], v[184:187], v[2:17]
	v_mfma_f32_32x32x16_bf16 v[50:65], v[192:195], v[188:191], v[50:65]
	v_mfma_f32_32x32x16_bf16 v[34:49], v[200:203], v[188:191], v[34:49]
	ds_read_b128 v[180:183], v138 offset:55360
	ds_read_b128 v[184:187], v133 offset:55360
	ds_read_b128 v[188:191], v133 offset:55392
	ds_read_b128 v[196:199], v138 offset:55392
	s_waitcnt lgkmcnt(4)
	v_mfma_f32_32x32x16_bf16 v[18:33], v[192:195], v[140:143], v[18:33]
	v_mfma_f32_32x32x16_bf16 v[2:17], v[200:203], v[140:143], v[2:17]
	ds_read_b128 v[192:195], v138 offset:59968
	ds_read_b128 v[140:143], v138 offset:60000
	s_waitcnt lgkmcnt(4)
	v_mfma_f32_32x32x16_bf16 v[50:65], v[180:183], v[184:187], v[50:65]
	s_waitcnt lgkmcnt(1)
	v_mfma_f32_32x32x16_bf16 v[34:49], v[192:195], v[184:187], v[34:49]
	ds_read_b128 v[184:187], v133 offset:59968
	ds_read_b128 v[146:149], v133 offset:60000
	s_waitcnt lgkmcnt(1)
	v_mfma_f32_32x32x16_bf16 v[18:33], v[180:183], v[184:187], v[18:33]
	v_mfma_f32_32x32x16_bf16 v[2:17], v[192:195], v[184:187], v[2:17]
	v_mfma_f32_32x32x16_bf16 v[50:65], v[196:199], v[188:191], v[50:65]
	v_mfma_f32_32x32x16_bf16 v[34:49], v[140:143], v[188:191], v[34:49]
	s_waitcnt lgkmcnt(0)
	v_mfma_f32_32x32x16_bf16 v[18:33], v[196:199], v[146:149], v[18:33]
	v_mfma_f32_32x32x16_bf16 v[2:17], v[140:143], v[146:149], v[2:17]
	s_cbranch_vccnz .LBB0_683
	s_waitcnt vmcnt(11)
	ds_write_b128 v128, v[90:93]
	s_waitcnt vmcnt(10)
	ds_write_b128 v129, v[94:97]
	s_waitcnt vmcnt(9)
	ds_write_b128 v128, v[98:101] offset:18432
	s_waitcnt vmcnt(8)
	ds_write_b128 v129, v[102:105] offset:18432
	s_waitcnt vmcnt(7)
	ds_write_b128 v130, v[106:109] offset:18432
	s_waitcnt vmcnt(6)
	ds_write_b128 v131, v[110:113] offset:18432
	s_branch .LBB0_683

; #define LAS __attribute__((address_space(3)))
; __device__ __forceinline__ void halo_gemm_unit(int unit, int tid, int lane, int wave, LAS unsigned char* lds, const bf16_t* __restrict__ XBp, const bf16_t* __restrict__ Wup, bf16_t* __restrict__ HALOp) {
;     ...
; #pragma unroll 1
;     for (int c = 0; c < 16; c += 2) {
;         { const int k2 = (c + 2 < 16) ? 64 * (c + 2) : 0;
; #pragma unroll
;           for (int i = 0; i < 2; ++i) ra0[i] = *(const v4u*)(gA[i] + k2);
; #pragma unroll
;           for (int i = 0; i < 4; ++i) rb0[i] = *(const v4u*)(gB[i] + k2);
;           HG_COMPUTE(lds);
; #pragma unroll
;           for (int i = 0; i < 2; ++i) *(LAS v4u*)(lds + HG_STAGE + lA[i]) = ra1[i];
; #pragma unroll
;           for (int i = 0; i < 4; ++i) *(LAS v4u*)(lds + HG_STAGE + lB[i]) = rb1[i];
;           __syncthreads(); }
;         { const int k3 = (c + 3 < 16) ? 64 * (c + 3) : 0;
; #pragma unroll
;           for (int i = 0; i < 2; ++i) ra1[i] = *(const v4u*)(gA[i] + k3);
; #pragma unroll
;           for (int i = 0; i < 4; ++i) rb1[i] = *(const v4u*)(gB[i] + k3);
;           HG_COMPUTE(lds + HG_STAGE);
;           if (c + 2 < 16) {
; #pragma unroll
;               for (int i = 0; i < 2; ++i) *(LAS v4u*)(lds + lA[i]) = ra0[i];
; #pragma unroll
;               for (int i = 0; i < 4; ++i) *(LAS v4u*)(lds + lB[i]) = rb0[i];
;           }
;           __syncthreads(); }
;     }
.LBB0_1756:
	s_cmp_gt_u32 s14, 13
	s_cselect_b64 s[10:11], -1, 0
	s_sub_i32 s0, s12, 64
	s_cmp_lt_u32 s14, 14
	s_cselect_b32 s8, s0, 0
	s_lshl_b64 s[0:1], s[8:9], 1
	s_cmp_lt_u32 s14, 13
	s_cselect_b32 s8, s12, 0
	v_lshl_add_u64 v[110:111], v[124:125], 0, s[0:1]
	v_lshl_add_u64 v[90:91], v[114:115], 0, s[0:1]
	v_lshl_add_u64 v[94:95], v[116:117], 0, s[0:1]
	v_lshl_add_u64 v[106:107], v[122:123], 0, s[0:1]
	v_lshl_add_u64 v[98:99], v[118:119], 0, s[0:1]
	v_lshl_add_u64 v[102:103], v[120:121], 0, s[0:1]
	global_load_dwordx4 v[90:93], v[90:91], off
	s_nop 0
	global_load_dwordx4 v[94:97], v[94:95], off
	s_nop 0
	global_load_dwordx4 v[98:101], v[98:99], off
	s_nop 0
	global_load_dwordx4 v[102:105], v[102:103], off
	s_nop 0
	global_load_dwordx4 v[106:109], v[106:107], off
	s_nop 0
	global_load_dwordx4 v[110:113], v[110:111], off
	s_nop 0
	v_add_u32_e32 v139, 0, v132
	ds_read_b128 v[156:159], v139 offset:18432
	ds_read_b128 v[160:163], v133
	ds_read_b128 v[164:167], v133 offset:32
	ds_read_b128 v[168:171], v139 offset:18464
	ds_read_b128 v[172:175], v139 offset:23040
	ds_read_b128 v[176:179], v139 offset:23072
	s_waitcnt lgkmcnt(4)
	v_mfma_f32_32x32x16_bf16 v[50:65], v[156:159], v[160:163], v[50:65]
	s_waitcnt lgkmcnt(1)
	v_mfma_f32_32x32x16_bf16 v[34:49], v[172:175], v[160:163], v[34:49]
	ds_read_b128 v[160:163], v133 offset:4608
	ds_read_b128 v[140:143], v133 offset:4640
	s_and_b64 vcc, exec, s[10:11]
	s_waitcnt lgkmcnt(1)
	v_mfma_f32_32x32x16_bf16 v[18:33], v[156:159], v[160:163], v[18:33]
	v_mfma_f32_32x32x16_bf16 v[2:17], v[172:175], v[160:163], v[2:17]
	v_mfma_f32_32x32x16_bf16 v[50:65], v[168:171], v[164:167], v[50:65]
	v_mfma_f32_32x32x16_bf16 v[34:49], v[176:179], v[164:167], v[34:49]
	s_waitcnt lgkmcnt(0)
	v_mfma_f32_32x32x16_bf16 v[18:33], v[168:171], v[140:143], v[18:33]
	ds_read_b128 v[156:159], v139 offset:18496
	ds_read_b128 v[160:163], v133 offset:64
	ds_read_b128 v[164:167], v133 offset:96
	ds_read_b128 v[168:171], v139 offset:18528
	v_mfma_f32_32x32x16_bf16 v[2:17], v[176:179], v[140:143], v[2:17]
	ds_read_b128 v[172:175], v139 offset:23104
	ds_read_b128 v[140:143], v139 offset:23136
	s_waitcnt lgkmcnt(4)
	v_mfma_f32_32x32x16_bf16 v[50:65], v[156:159], v[160:163], v[50:65]
	s_waitcnt lgkmcnt(1)
	v_mfma_f32_32x32x16_bf16 v[34:49], v[172:175], v[160:163], v[34:49]
	ds_read_b128 v[160:163], v133 offset:4672
	ds_read_b128 v[144:147], v133 offset:4704
	s_waitcnt lgkmcnt(1)
	v_mfma_f32_32x32x16_bf16 v[18:33], v[156:159], v[160:163], v[18:33]
	v_mfma_f32_32x32x16_bf16 v[2:17], v[172:175], v[160:163], v[2:17]
	v_mfma_f32_32x32x16_bf16 v[50:65], v[168:171], v[164:167], v[50:65]
	v_mfma_f32_32x32x16_bf16 v[34:49], v[140:143], v[164:167], v[34:49]
	s_waitcnt lgkmcnt(0)
	v_mfma_f32_32x32x16_bf16 v[18:33], v[168:171], v[144:147], v[18:33]
	s_waitcnt vmcnt(11)
	ds_write_b128 v128, v[66:69] offset:55296
	s_waitcnt vmcnt(10)
	ds_write_b128 v129, v[70:73] offset:55296
	s_waitcnt vmcnt(9)
	ds_write_b128 v134, v[74:77] offset:55296
	s_waitcnt vmcnt(8)
	ds_write_b128 v135, v[78:81] offset:55296
	s_waitcnt vmcnt(6)
	ds_write_b128 v136, v[86:89] offset:55296
	ds_write_b128 v137, v[82:85] offset:55296
	s_waitcnt lgkmcnt(0)
	s_barrier
	s_lshl_b64 s[0:1], s[8:9], 1
	v_lshl_add_u64 v[148:149], v[124:125], 0, s[0:1]
	v_lshl_add_u64 v[86:87], v[122:123], 0, s[0:1]
	v_lshl_add_u64 v[66:67], v[114:115], 0, s[0:1]
	v_lshl_add_u64 v[70:71], v[116:117], 0, s[0:1]
	v_lshl_add_u64 v[78:79], v[120:121], 0, s[0:1]
	v_lshl_add_u64 v[74:75], v[118:119], 0, s[0:1]
	global_load_dwordx4 v[66:69], v[66:67], off
	s_nop 0
	global_load_dwordx4 v[70:73], v[70:71], off
	s_nop 0
	global_load_dwordx4 v[74:77], v[74:75], off
	s_nop 0
	global_load_dwordx4 v[78:81], v[78:79], off
	s_nop 0
	global_load_dwordx4 v[86:89], v[86:87], off
	s_nop 0
	global_load_dwordx4 v[82:85], v[148:149], off
	s_nop 0
	v_mfma_f32_32x32x16_bf16 v[2:17], v[140:143], v[144:147], v[2:17]
	ds_read_b128 v[180:183], v138 offset:55296
	ds_read_b128 v[184:187], v133 offset:55296
	ds_read_b128 v[188:191], v133 offset:55328
	ds_read_b128 v[192:195], v138 offset:55328
	ds_read_b128 v[196:199], v138 offset:59904
	ds_read_b128 v[200:203], v138 offset:59936
	s_waitcnt lgkmcnt(4)
	v_mfma_f32_32x32x16_bf16 v[50:65], v[180:183], v[184:187], v[50:65]
	s_waitcnt lgkmcnt(1)
	v_mfma_f32_32x32x16_bf16 v[34:49], v[196:199], v[184:187], v[34:49]
	ds_read_b128 v[184:187], v133 offset:59904
	ds_read_b128 v[140:143], v133 offset:59936
	s_waitcnt lgkmcnt(1)
	v_mfma_f32_32x32x16_bf16 v[18:33], v[180:183], v[184:187], v[18:33]
	v_mfma_f32_32x32x16_bf16 v[2:17], v[196:199], v[184:187], v[2:17]
	v_mfma_f32_32x32x16_bf16 v[50:65], v[192:195], v[188:191], v[50:65]
	v_mfma_f32_32x32x16_bf16 v[34:49], v[200:203], v[188:191], v[34:49]
	ds_read_b128 v[180:183], v138 offset:55360
	ds_read_b128 v[184:187], v133 offset:55360
	ds_read_b128 v[188:191], v133 offset:55392
	ds_read_b128 v[196:199], v138 offset:55392
	s_waitcnt lgkmcnt(4)
	v_mfma_f32_32x32x16_bf16 v[18:33], v[192:195], v[140:143], v[18:33]
	v_mfma_f32_32x32x16_bf16 v[2:17], v[200:203], v[140:143], v[2:17]
	ds_read_b128 v[192:195], v138 offset:59968
	ds_read_b128 v[140:143], v138 offset:60000
	s_waitcnt lgkmcnt(4)
	v_mfma_f32_32x32x16_bf16 v[50:65], v[180:183], v[184:187], v[50:65]
	s_waitcnt lgkmcnt(1)
	v_mfma_f32_32x32x16_bf16 v[34:49], v[192:195], v[184:187], v[34:49]
	ds_read_b128 v[184:187], v133 offset:59968
	ds_read_b128 v[144:147], v133 offset:60000
	s_waitcnt lgkmcnt(1)
	v_mfma_f32_32x32x16_bf16 v[18:33], v[180:183], v[184:187], v[18:33]
	v_mfma_f32_32x32x16_bf16 v[2:17], v[192:195], v[184:187], v[2:17]
	v_mfma_f32_32x32x16_bf16 v[50:65], v[196:199], v[188:191], v[50:65]
	v_mfma_f32_32x32x16_bf16 v[34:49], v[140:143], v[188:191], v[34:49]
	s_waitcnt lgkmcnt(0)
	v_mfma_f32_32x32x16_bf16 v[18:33], v[196:199], v[144:147], v[18:33]
	v_mfma_f32_32x32x16_bf16 v[2:17], v[140:143], v[144:147], v[2:17]
	s_cbranch_vccnz .LBB0_1755
	s_waitcnt vmcnt(11)
	ds_write_b128 v128, v[90:93]
	s_waitcnt vmcnt(10)
	ds_write_b128 v129, v[94:97]
	s_waitcnt vmcnt(9)
	ds_write_b128 v128, v[98:101] offset:18432
	s_waitcnt vmcnt(8)
	ds_write_b128 v129, v[102:105] offset:18432
	s_waitcnt vmcnt(7)
	ds_write_b128 v130, v[106:109] offset:18432
	s_waitcnt vmcnt(6)
	ds_write_b128 v131, v[110:113] offset:18432
	s_branch .LBB0_1755
